# gate-up: first two K-loop waits of each unit relaxed to vmcnt(16) so the epilogue's 8 stores do not gate the next unit's first phases; phase prologue drains fully
# baseline (speedup 1.0000x reference)
; #define PG8_STAGE(bufoff, gbase, voff) do { _Pragma("unroll") for (int _i = 0; _i < 2; ++_i) \
;         __builtin_amdgcn_global_load_lds((const unsigned*)((const char*)(gbase) + (voff)[_i]), (PG8_LAS unsigned*)(lds + (bufoff) + ldsw + _i * 8192), 16, 0, 0); } while (0)
; #define PG8_WAIT_V(n) asm volatile("s_waitcnt vmcnt(" #n ")" ::: "memory")
; #define PG8_BAR __builtin_amdgcn_s_barrier()
; template <class Epi, class Sched, bool ALIGN_EPI = false, bool SP2 = false>
; __device__ __forceinline__ void gemm_phase(PG8_LAS unsigned char* lds, const Gemm g, const Sched& S, const Epi& E) {
;     ...
;     if constexpr (SP2) {
;         PG8_STAGE(PG8_SB(0, 0), cB, voffB); PG8_STAGE(PG8_SB(0, 1), cB + hstep, voffB); PG8_STAGE(PG8_SA(0, 0), cA, voffA); PG8_STAGE(PG8_SA(0, 1), cA + hstep, voffA);
;         if (wr == 1) PG8_BAR;
;         PG8_WAIT_V(2); PG8_BAR;
;         PG8_STAGE(PG8_SB(1, 0), cB + kstep, voffB); PG8_STAGE(PG8_SA(1, 0), cA + kstep, voffA); PG8_STAGE(PG8_SB(1, 1), cB + hstep + kstep, voffB);
;         PG8_WAIT_V(6); PG8_BAR;
.LBB0_41:
	v_bfe_u32 v185, v16, 4, 2
	v_and_b32_e32 v184, 15, v16
	v_lshlrev_b32_e32 v17, 4, v185
	v_lshlrev_b32_e32 v16, 2, v16
	v_lshl_or_b32 v17, v184, 6, v17
	s_lshl_b32 s1, s38, 13
	v_and_b32_e32 v16, 32, v16
	s_waitcnt lgkmcnt(0)
	v_bitop3_b32 v18, v17, s1, v16 bitop3:0xde
	s_lshl_b32 s1, s23, 5
	s_and_b32 s1, s1, 0x60
	s_add_i32 m0, s43, 0x18000
	v_lshl_add_u64 v[8:9], v[8:9], 0, s[26:27]
	s_lshl_b32 s68, s38, 6
	s_lshl_b32 s23, s1, 7
	s_waitcnt vmcnt(2)
	s_barrier
	global_load_lds_dwordx4 v[8:9], off
	v_lshl_add_u64 v[6:7], v[6:7], 0, s[26:27]
	s_add_i32 m0, s43, 0x1a000
	s_add_i32 s69, s43, 0x8000
	s_add_i32 s72, s43, 0xa000
	global_load_lds_dwordx4 v[6:7], off
	v_lshl_add_u64 v[2:3], v[2:3], 0, s[26:27]
	s_mov_b32 m0, s69
	s_add_u32 s30, s36, 0x40080
	global_load_lds_dwordx4 v[2:3], off
	v_lshl_add_u64 v[2:3], v[4:5], 0, s[26:27]
	s_mov_b32 m0, s72
	s_addc_u32 s31, s37, 0
	global_load_lds_dwordx4 v[2:3], off
	s_add_i32 m0, s43, 0x1c000
	v_lshl_add_u64 v[2:3], s[30:31], 0, v[0:1]
	global_load_lds_dwordx4 v[2:3], off
	v_lshl_add_u64 v[2:3], s[30:31], 0, v[162:163]
	s_add_i32 m0, s43, 0x1e000
	s_cmpk_lt_u32 s21, 0x100
	global_load_lds_dwordx4 v[2:3], off
	v_lshlrev_b32_e32 v2, 14, v13
	v_and_b32_e32 v2, 0xffff8000, v2
	v_lshl_add_u32 v2, v14, 11, v2
	v_and_b32_e32 v3, 1, v13
	v_lshl_or_b32 v2, v3, 6, v2
	v_lshl_add_u32 v164, v15, 1, v2
	v_lshlrev_b32_e32 v2, 14, v10
	v_and_b32_e32 v2, 0xffff8000, v2
	s_waitcnt vmcnt(0)
	v_lshl_add_u32 v2, v11, 11, v2
	v_and_b32_e32 v3, 1, v10
	v_lshl_or_b32 v2, v3, 6, v2
	s_sext_i32_i16 s44, s24
	v_bitop3_b32 v186, v17, s23, v16 bitop3:0xde
	s_cselect_b64 s[50:51], -1, 0
	s_ashr_i32 s73, s67, 31
	s_mov_b32 s41, s25
	v_mov_b32_e32 v165, v1
	v_lshl_add_u32 v166, v12, 1, v2
	v_mov_b32_e32 v167, v1
	s_mov_b32 s92, 0
	s_lshl_b32 s24, s1, 1
	v_add_u32_e32 v187, 0, v18
	s_barrier
	s_branch .LBB0_44

; #define PG8_MMA(ai, bj, At, Bt) do { __builtin_amdgcn_s_setprio(1); _Pragma("unroll") for (int m = 0; m < 4; ++m) _Pragma("unroll") for (int n = 0; n < 2; ++n) _Pragma("unroll") for (int k = 0; k < 2; ++k) \
;         acc[ai][bj][m][n] = __builtin_amdgcn_mfma_f32_16x16x32_bf16(Bt[n][k], At[m][k], acc[ai][bj][m][n], 0, 0, 0); __builtin_amdgcn_s_setprio(0); } while (0)
; template <class Epi, class Sched, bool ALIGN_EPI = false, bool SP2 = false>
; __device__ __forceinline__ void gemm_phase(PG8_LAS unsigned char* lds, const Gemm g, const Sched& S, const Epi& E) {
;     ...
;         { int t = 0;
;           if constexpr (Epi::KEEP_ACC) PG8_ITER(PG8_MMA); else PG8_ITER(PG8_MMAZ); }
.LBB0_46:
	s_ashr_i32 s55, s54, 31
	s_lshl_b64 s[30:31], s[54:55], 19
	v_readlane_b32 s48, v253, 9
	v_readlane_b32 s49, v253, 10
	s_add_u32 s56, s48, s30
	s_addc_u32 s57, s49, s31
	s_ashr_i32 s53, s52, 31
	s_lshl_b64 s[30:31], s[52:53], 19
	s_add_u32 s58, s2, s30
	s_addc_u32 s59, s20, s31
	s_add_i32 s93, 0, 0x10000
	s_and_b64 s[30:31], s[38:39], exec
	s_cselect_b32 s1, s57, s61
	s_cselect_b32 s45, s56, s60
	s_add_i32 s95, 0, 0x14000
	v_add_u32_e32 v130, s93, v186
	v_add_u32_e32 v131, s95, v186
	ds_read_b128 v[2:5], v130
	ds_read_b128 v[6:9], v130 offset:1024
	ds_read_b128 v[10:13], v130 offset:2048
	ds_read_b128 v[14:17], v130 offset:3072
	ds_read_b128 v[18:21], v131
	ds_read_b128 v[22:25], v131 offset:1024
	ds_read_b128 v[26:29], v131 offset:2048
	ds_read_b128 v[30:33], v131 offset:3072
	s_and_b64 s[30:31], s[38:39], exec
	s_cselect_b32 s53, s59, s37
	s_cselect_b32 s55, s58, s36
	s_add_u32 s30, s60, 0x40080
	s_addc_u32 s31, s61, 0
	s_add_i32 s70, s43, 0xc000
	v_lshl_add_u64 v[66:67], s[30:31], 0, v[0:1]
	s_mov_b32 m0, s70
	s_add_i32 s71, s43, 0xe000
	ds_read_b128 v[34:37], v187
	ds_read_b128 v[38:41], v187 offset:1024
	ds_read_b128 v[42:45], v187 offset:2048
	ds_read_b128 v[46:49], v187 offset:3072
	ds_read_b128 v[50:53], v187 offset:4096
	ds_read_b128 v[54:57], v187 offset:5120
	ds_read_b128 v[58:61], v187 offset:6144
	ds_read_b128 v[62:65], v187 offset:7168
	global_load_lds_dwordx4 v[66:67], off
	v_lshl_add_u64 v[66:67], s[30:31], 0, v[162:163]
	s_mov_b32 m0, s71
	s_nop 0
	global_load_lds_dwordx4 v[66:67], off
	s_waitcnt vmcnt(16)
	s_waitcnt lgkmcnt(0)
	s_barrier
	s_setprio 1
	s_waitcnt lgkmcnt(0)
	v_mfma_f32_16x16x32_bf16 v[90:93], v[2:5], v[58:61], 0
	v_mfma_f32_16x16x32_bf16 v[66:69], v[2:5], v[34:37], 0
	v_mfma_f32_16x16x32_bf16 v[70:73], v[10:13], v[34:37], 0
	v_mfma_f32_16x16x32_bf16 v[74:77], v[2:5], v[42:45], 0
	v_mfma_f32_16x16x32_bf16 v[78:81], v[10:13], v[42:45], 0
	v_mfma_f32_16x16x32_bf16 v[82:85], v[2:5], v[50:53], 0
	v_mfma_f32_16x16x32_bf16 v[86:89], v[10:13], v[50:53], 0
	v_mfma_f32_16x16x32_bf16 v[94:97], v[6:9], v[62:65], v[90:93]
	v_mfma_f32_16x16x32_bf16 v[90:93], v[10:13], v[58:61], 0
	v_mfma_f32_16x16x32_bf16 v[66:69], v[6:9], v[38:41], v[66:69]
	v_mfma_f32_16x16x32_bf16 v[70:73], v[14:17], v[38:41], v[70:73]
	v_mfma_f32_16x16x32_bf16 v[74:77], v[6:9], v[46:49], v[74:77]
	v_mfma_f32_16x16x32_bf16 v[78:81], v[14:17], v[46:49], v[78:81]
	v_mfma_f32_16x16x32_bf16 v[82:85], v[6:9], v[54:57], v[82:85]
	v_mfma_f32_16x16x32_bf16 v[86:89], v[14:17], v[54:57], v[86:89]
	v_mfma_f32_16x16x32_bf16 v[102:105], v[14:17], v[62:65], v[90:93]
	s_setprio 0
	s_setprio 1
	v_mfma_f32_16x16x32_bf16 v[90:93], v[18:21], v[34:37], 0
	v_mfma_f32_16x16x32_bf16 v[34:37], v[26:29], v[34:37], 0
	v_mfma_f32_16x16x32_bf16 v[110:113], v[22:25], v[38:41], v[90:93]
	v_mfma_f32_16x16x32_bf16 v[34:37], v[30:33], v[38:41], v[34:37]
	v_mfma_f32_16x16x32_bf16 v[38:41], v[18:21], v[42:45], 0
	v_mfma_f32_16x16x32_bf16 v[42:45], v[26:29], v[42:45], 0
	v_mfma_f32_16x16x32_bf16 v[38:41], v[22:25], v[46:49], v[38:41]
	v_mfma_f32_16x16x32_bf16 v[42:45], v[30:33], v[46:49], v[42:45]
	v_mfma_f32_16x16x32_bf16 v[46:49], v[18:21], v[50:53], 0
	v_mfma_f32_16x16x32_bf16 v[50:53], v[26:29], v[50:53], 0
	v_mfma_f32_16x16x32_bf16 v[46:49], v[22:25], v[54:57], v[46:49]
	v_mfma_f32_16x16x32_bf16 v[50:53], v[30:33], v[54:57], v[50:53]
	v_mfma_f32_16x16x32_bf16 v[54:57], v[18:21], v[58:61], 0
	v_mfma_f32_16x16x32_bf16 v[58:61], v[26:29], v[58:61], 0
	v_mfma_f32_16x16x32_bf16 v[54:57], v[22:25], v[62:65], v[54:57]
	v_mfma_f32_16x16x32_bf16 v[58:61], v[30:33], v[62:65], v[58:61]
	s_setprio 0
	s_barrier
	s_add_i32 s93, s93, s34
	v_lshl_add_u64 v[200:201], s[36:37], 0, v[0:1]
	s_mov_b64 s[48:49], 0x100
	s_add_i32 s94, s93, 0x2000
	v_lshl_add_u64 v[132:133], v[200:201], 0, s[48:49]
	s_mov_b32 m0, s93
	v_lshl_add_u64 v[204:205], s[36:37], 0, v[162:163]
	s_add_u32 s30, s36, 0x40100
	ds_read_b128 v[62:65], v187 offset:16384
	ds_read_b128 v[90:93], v187 offset:17408
	ds_read_b128 v[98:101], v187 offset:18432
	ds_read_b128 v[106:109], v187 offset:19456
	ds_read_b128 v[114:117], v187 offset:20480
	ds_read_b128 v[118:121], v187 offset:21504
	ds_read_b128 v[122:125], v187 offset:22528
	ds_read_b128 v[126:129], v187 offset:23552
	global_load_lds_dwordx4 v[132:133], off
	v_lshl_add_u64 v[132:133], v[204:205], 0, s[48:49]
	s_mov_b32 m0, s94
	s_addc_u32 s31, s37, 0
	s_add_i32 s95, s95, s34
	global_load_lds_dwordx4 v[132:133], off
	v_lshl_add_u64 v[132:133], s[30:31], 0, v[0:1]
	s_mov_b32 m0, s95
	s_add_i32 s96, s95, 0x2000
	global_load_lds_dwordx4 v[132:133], off
	v_lshl_add_u64 v[132:133], s[30:31], 0, v[162:163]
	s_mov_b32 m0, s96
	v_lshl_add_u64 v[208:209], s[60:61], 0, v[0:1]
	global_load_lds_dwordx4 v[132:133], off
	v_lshl_add_u64 v[132:133], v[208:209], 0, s[48:49]
	s_mov_b32 m0, s43
	v_lshl_add_u64 v[246:247], s[60:61], 0, v[162:163]
	global_load_lds_dwordx4 v[132:133], off
	v_lshl_add_u64 v[132:133], v[246:247], 0, s[48:49]
	s_mov_b32 m0, s64
	s_nop 0
	global_load_lds_dwordx4 v[132:133], off
	s_waitcnt vmcnt(16)
	s_waitcnt lgkmcnt(0)
	s_barrier
	s_setprio 1
	s_waitcnt lgkmcnt(0)
	v_mfma_f32_16x16x32_bf16 v[132:135], v[2:5], v[62:65], 0
	v_mfma_f32_16x16x32_bf16 v[142:145], v[2:5], v[98:101], 0
	v_mfma_f32_16x16x32_bf16 v[150:153], v[2:5], v[114:117], 0
	v_mfma_f32_16x16x32_bf16 v[2:5], v[2:5], v[122:125], 0
	v_mfma_f32_16x16x32_bf16 v[134:137], v[6:9], v[90:93], v[132:135]
	v_mfma_f32_16x16x32_bf16 v[142:145], v[6:9], v[106:109], v[142:145]
	v_mfma_f32_16x16x32_bf16 v[150:153], v[6:9], v[118:121], v[150:153]
	v_mfma_f32_16x16x32_bf16 v[2:5], v[6:9], v[126:129], v[2:5]
	v_mfma_f32_16x16x32_bf16 v[6:9], v[10:13], v[122:125], 0
	v_mfma_f32_16x16x32_bf16 v[138:141], v[10:13], v[62:65], 0
	v_mfma_f32_16x16x32_bf16 v[146:149], v[10:13], v[98:101], 0
	v_mfma_f32_16x16x32_bf16 v[154:157], v[10:13], v[114:117], 0
	v_mfma_f32_16x16x32_bf16 v[6:9], v[14:17], v[126:129], v[6:9]
	v_mfma_f32_16x16x32_bf16 v[138:141], v[14:17], v[90:93], v[138:141]
	v_mfma_f32_16x16x32_bf16 v[146:149], v[14:17], v[106:109], v[146:149]
	v_mfma_f32_16x16x32_bf16 v[154:157], v[14:17], v[118:121], v[154:157]
	s_setprio 0
	s_setprio 1
	v_mfma_f32_16x16x32_bf16 v[10:13], v[18:21], v[62:65], 0
	v_mfma_f32_16x16x32_bf16 v[14:17], v[22:25], v[90:93], v[10:13]
	v_mfma_f32_16x16x32_bf16 v[10:13], v[26:29], v[62:65], 0
	v_mfma_f32_16x16x32_bf16 v[158:161], v[30:33], v[90:93], v[10:13]
	v_mfma_f32_16x16x32_bf16 v[10:13], v[18:21], v[98:101], 0
	v_mfma_f32_16x16x32_bf16 v[168:171], v[22:25], v[106:109], v[10:13]
	v_mfma_f32_16x16x32_bf16 v[10:13], v[26:29], v[98:101], 0
	v_mfma_f32_16x16x32_bf16 v[172:175], v[30:33], v[106:109], v[10:13]
	v_mfma_f32_16x16x32_bf16 v[10:13], v[18:21], v[114:117], 0
	v_mfma_f32_16x16x32_bf16 v[176:179], v[22:25], v[118:121], v[10:13]
	v_mfma_f32_16x16x32_bf16 v[10:13], v[26:29], v[114:117], 0
	v_mfma_f32_16x16x32_bf16 v[180:183], v[30:33], v[118:121], v[10:13]
	v_mfma_f32_16x16x32_bf16 v[10:13], v[18:21], v[122:125], 0
	v_mfma_f32_16x16x32_bf16 v[188:191], v[22:25], v[126:129], v[10:13]
	v_mfma_f32_16x16x32_bf16 v[10:13], v[26:29], v[122:125], 0
	v_mfma_f32_16x16x32_bf16 v[192:195], v[30:33], v[126:129], v[10:13]
	s_setprio 0
	s_barrier
	s_add_i32 s97, 0, 0x18000
	s_add_i32 vcc_hi, 0, 0x1c000
	v_add_u32_e32 v132, s97, v186
	v_add_u32_e32 v133, vcc_hi, v186
	s_nop 0
	ds_read_b128 v[10:13], v132
	ds_read_b128 v[22:25], v132 offset:1024
	ds_read_b128 v[30:33], v132 offset:2048
	ds_read_b128 v[62:65], v132 offset:3072
	ds_read_b128 v[196:199], v133
	ds_read_b128 v[210:213], v133 offset:1024
	ds_read_b128 v[214:217], v133 offset:2048
	ds_read_b128 v[218:221], v133 offset:3072
	s_add_u32 s30, s60, 0x40100
	s_addc_u32 s31, s61, 0
	s_mov_b32 m0, s65
	v_lshl_add_u64 v[90:91], s[30:31], 0, v[0:1]
	ds_read_b128 v[18:21], v187 offset:32768
	ds_read_b128 v[26:29], v187 offset:33792
	ds_read_b128 v[222:225], v187 offset:34816
	ds_read_b128 v[226:229], v187 offset:35840
	ds_read_b128 v[230:233], v187 offset:36864
	ds_read_b128 v[234:237], v187 offset:37888
	ds_read_b128 v[238:241], v187 offset:38912
	ds_read_b128 v[242:245], v187 offset:39936
	global_load_lds_dwordx4 v[90:91], off
	v_lshl_add_u64 v[90:91], s[30:31], 0, v[162:163]
	s_mov_b32 m0, s66
	s_nop 0
	global_load_lds_dwordx4 v[90:91], off
	s_waitcnt vmcnt(8)
	s_waitcnt lgkmcnt(0)
	s_barrier
	s_setprio 1
	s_waitcnt lgkmcnt(0)
	v_mfma_f32_16x16x32_bf16 v[66:69], v[10:13], v[18:21], v[66:69]
	v_mfma_f32_16x16x32_bf16 v[122:125], v[22:25], v[26:29], v[66:69]
	v_mfma_f32_16x16x32_bf16 v[66:69], v[30:33], v[18:21], v[70:73]
	v_mfma_f32_16x16x32_bf16 v[114:117], v[62:65], v[26:29], v[66:69]
	v_mfma_f32_16x16x32_bf16 v[66:69], v[10:13], v[222:225], v[74:77]
	v_mfma_f32_16x16x32_bf16 v[106:109], v[22:25], v[226:229], v[66:69]
	v_mfma_f32_16x16x32_bf16 v[66:69], v[30:33], v[222:225], v[78:81]
	v_mfma_f32_16x16x32_bf16 v[98:101], v[62:65], v[226:229], v[66:69]
	v_mfma_f32_16x16x32_bf16 v[66:69], v[10:13], v[230:233], v[82:85]
	v_mfma_f32_16x16x32_bf16 v[90:93], v[22:25], v[234:237], v[66:69]
	v_mfma_f32_16x16x32_bf16 v[66:69], v[30:33], v[230:233], v[86:89]
	v_mfma_f32_16x16x32_bf16 v[82:85], v[62:65], v[234:237], v[66:69]
	v_mfma_f32_16x16x32_bf16 v[66:69], v[10:13], v[238:241], v[94:97]
	v_mfma_f32_16x16x32_bf16 v[74:77], v[22:25], v[242:245], v[66:69]
	v_mfma_f32_16x16x32_bf16 v[66:69], v[30:33], v[238:241], v[102:105]
	v_mfma_f32_16x16x32_bf16 v[66:69], v[62:65], v[242:245], v[66:69]
	s_setprio 0
	s_setprio 1
	v_mfma_f32_16x16x32_bf16 v[70:73], v[196:199], v[18:21], v[110:113]
	v_mfma_f32_16x16x32_bf16 v[18:21], v[214:217], v[18:21], v[34:37]
	v_mfma_f32_16x16x32_bf16 v[118:121], v[218:221], v[26:29], v[18:21]
	v_mfma_f32_16x16x32_bf16 v[18:21], v[196:199], v[222:225], v[38:41]
	v_mfma_f32_16x16x32_bf16 v[110:113], v[210:213], v[226:229], v[18:21]
	v_mfma_f32_16x16x32_bf16 v[18:21], v[214:217], v[222:225], v[42:45]
	v_mfma_f32_16x16x32_bf16 v[102:105], v[218:221], v[226:229], v[18:21]
	v_mfma_f32_16x16x32_bf16 v[18:21], v[196:199], v[230:233], v[46:49]
	v_mfma_f32_16x16x32_bf16 v[94:97], v[210:213], v[234:237], v[18:21]
	v_mfma_f32_16x16x32_bf16 v[18:21], v[214:217], v[230:233], v[50:53]
	v_mfma_f32_16x16x32_bf16 v[86:89], v[218:221], v[234:237], v[18:21]
	v_mfma_f32_16x16x32_bf16 v[18:21], v[196:199], v[238:241], v[54:57]
	v_mfma_f32_16x16x32_bf16 v[78:81], v[210:213], v[242:245], v[18:21]
	v_mfma_f32_16x16x32_bf16 v[18:21], v[214:217], v[238:241], v[58:61]
	v_mfma_f32_16x16x32_bf16 v[126:129], v[210:213], v[26:29], v[70:73]
	v_mfma_f32_16x16x32_bf16 v[70:73], v[218:221], v[242:245], v[18:21]
	s_setprio 0
	s_barrier
; #define PG8_MMA(ai, bj, At, Bt) do { __builtin_amdgcn_s_setprio(1); _Pragma("unroll") for (int m = 0; m < 4; ++m) _Pragma("unroll") for (int n = 0; n < 2; ++n) _Pragma("unroll") for (int k = 0; k < 2; ++k) \
;         acc[ai][bj][m][n] = __builtin_amdgcn_mfma_f32_16x16x32_bf16(Bt[n][k], At[m][k], acc[ai][bj][m][n], 0, 0, 0); __builtin_amdgcn_s_setprio(0); } while (0)
; template <class Epi, class Sched, bool ALIGN_EPI = false, bool SP2 = false>
; __device__ __forceinline__ void gemm_phase(PG8_LAS unsigned char* lds, const Gemm g, const Sched& S, const Epi& E) {
;     ...
;         for (int t = 2; t < nt; t += 2) PG8_ITER(PG8_MMA);
	s_add_i32 s97, s97, s34
	s_mov_b64 s[62:63], 0x180
	s_add_i32 vcc_lo, s97, 0x2000
	s_nop 0
	v_lshl_add_u64 v[18:19], v[200:201], 0, s[62:63]
	s_mov_b32 m0, s97
	s_add_u32 s30, s36, 0x40180
	ds_read_b128 v[38:41], v187 offset:49152
	ds_read_b128 v[46:49], v187 offset:50176
	ds_read_b128 v[222:225], v187 offset:51200
	ds_read_b128 v[226:229], v187 offset:52224
	ds_read_b128 v[230:233], v187 offset:53248
	ds_read_b128 v[234:237], v187 offset:54272
	ds_read_b128 v[238:241], v187 offset:55296
	ds_read_b128 v[242:245], v187 offset:56320
	global_load_lds_dwordx4 v[18:19], off
	v_lshl_add_u64 v[18:19], v[204:205], 0, s[62:63]
	s_mov_b32 m0, vcc_lo
	s_addc_u32 s31, s37, 0
	s_add_i32 vcc_hi, vcc_hi, s34
	global_load_lds_dwordx4 v[18:19], off
	v_lshl_add_u64 v[18:19], s[30:31], 0, v[0:1]
	s_mov_b32 m0, vcc_hi
	s_add_i32 s48, vcc_hi, 0x2000
	global_load_lds_dwordx4 v[18:19], off
	v_lshl_add_u64 v[18:19], s[30:31], 0, v[162:163]
	s_mov_b32 m0, s48
	s_nop 0
	global_load_lds_dwordx4 v[18:19], off
	v_lshl_add_u64 v[18:19], v[208:209], 0, s[62:63]
	s_mov_b32 m0, s69
	s_nop 0
	global_load_lds_dwordx4 v[18:19], off
	v_lshl_add_u64 v[18:19], v[246:247], 0, s[62:63]
	s_mov_b32 m0, s72
	s_nop 0
	global_load_lds_dwordx4 v[18:19], off
	s_waitcnt vmcnt(8)
	s_waitcnt lgkmcnt(0)
	s_barrier
	s_setprio 1
	s_waitcnt lgkmcnt(0)
	v_mfma_f32_16x16x32_bf16 v[18:21], v[10:13], v[38:41], v[134:137]
	v_mfma_f32_16x16x32_bf16 v[58:61], v[22:25], v[46:49], v[18:21]
	v_mfma_f32_16x16x32_bf16 v[18:21], v[30:33], v[38:41], v[138:141]
	v_mfma_f32_16x16x32_bf16 v[50:53], v[62:65], v[46:49], v[18:21]
	v_mfma_f32_16x16x32_bf16 v[18:21], v[10:13], v[222:225], v[142:145]
	v_mfma_f32_16x16x32_bf16 v[42:45], v[22:25], v[226:229], v[18:21]
	v_mfma_f32_16x16x32_bf16 v[18:21], v[30:33], v[222:225], v[146:149]
	v_mfma_f32_16x16x32_bf16 v[34:37], v[62:65], v[226:229], v[18:21]
	v_mfma_f32_16x16x32_bf16 v[18:21], v[10:13], v[230:233], v[150:153]
	v_mfma_f32_16x16x32_bf16 v[2:5], v[10:13], v[238:241], v[2:5]
	v_mfma_f32_16x16x32_bf16 v[26:29], v[22:25], v[234:237], v[18:21]
	v_mfma_f32_16x16x32_bf16 v[18:21], v[30:33], v[230:233], v[154:157]
	v_mfma_f32_16x16x32_bf16 v[10:13], v[22:25], v[242:245], v[2:5]
	v_mfma_f32_16x16x32_bf16 v[2:5], v[30:33], v[238:241], v[6:9]
	v_mfma_f32_16x16x32_bf16 v[18:21], v[62:65], v[234:237], v[18:21]
	v_mfma_f32_16x16x32_bf16 v[2:5], v[62:65], v[242:245], v[2:5]
	s_setprio 0
	s_setprio 1
	v_mfma_f32_16x16x32_bf16 v[6:9], v[196:199], v[38:41], v[14:17]
	v_mfma_f32_16x16x32_bf16 v[62:65], v[210:213], v[46:49], v[6:9]
	v_mfma_f32_16x16x32_bf16 v[6:9], v[214:217], v[38:41], v[158:161]
	v_mfma_f32_16x16x32_bf16 v[54:57], v[218:221], v[46:49], v[6:9]
	v_mfma_f32_16x16x32_bf16 v[6:9], v[196:199], v[222:225], v[168:171]
	v_mfma_f32_16x16x32_bf16 v[46:49], v[210:213], v[226:229], v[6:9]
	v_mfma_f32_16x16x32_bf16 v[6:9], v[214:217], v[222:225], v[172:175]
	v_mfma_f32_16x16x32_bf16 v[38:41], v[218:221], v[226:229], v[6:9]
	v_mfma_f32_16x16x32_bf16 v[6:9], v[196:199], v[230:233], v[176:179]
	v_mfma_f32_16x16x32_bf16 v[30:33], v[210:213], v[234:237], v[6:9]
	v_mfma_f32_16x16x32_bf16 v[6:9], v[214:217], v[230:233], v[180:183]
	v_mfma_f32_16x16x32_bf16 v[22:25], v[218:221], v[234:237], v[6:9]
	v_mfma_f32_16x16x32_bf16 v[6:9], v[196:199], v[238:241], v[188:191]
	v_mfma_f32_16x16x32_bf16 v[14:17], v[210:213], v[242:245], v[6:9]
	v_mfma_f32_16x16x32_bf16 v[6:9], v[214:217], v[238:241], v[192:195]
	v_mfma_f32_16x16x32_bf16 v[6:9], v[218:221], v[242:245], v[6:9]
	s_setprio 0
	s_barrier
	s_add_u32 s60, s60, 0x40180
	s_addc_u32 s61, s61, 0
	s_add_u32 s23, s36, 0x200
	s_addc_u32 s49, s37, 0
	s_mov_b32 s21, 0
